# radix bit loop: 10-register variant when candidate count <= 640
# speedup vs baseline: 1.0088x; 1.0013x over previous
.LBB0_469:
	s_andn2_saveexec_b64 s[58:59], s[6:7]
	s_cbranch_execz .LBB0_463
	s_movk_i32 s4, 0xffc
	v_mad_u64_u32 v[0:1], s[4:5], v19, s4, v[0:1]
	v_mov_b32_e32 v1, 0
	v_mov_b32_e32 v3, 0
	s_and_saveexec_b64 s[4:5], vcc
	v_lshl_add_u32 v3, v156, 2, v0
	ds_read_b32 v3, v3
	s_or_b64 exec, exec, s[4:5]
	v_cmp_ge_i32_e64 s[4:5], v182, v18
	v_cmp_lt_i32_e32 vcc, v182, v18
	s_and_saveexec_b64 s[6:7], vcc
	v_lshl_add_u32 v1, v156, 2, v0
	ds_read_b32 v1, v1 offset:256
	s_or_b64 exec, exec, s[6:7]
	v_cmp_ge_i32_e64 s[74:75], v183, v18
	v_cmp_lt_i32_e32 vcc, v183, v18
	v_mov_b32_e32 v4, 0
	v_mov_b32_e32 v5, 0
	s_and_saveexec_b64 s[6:7], vcc
	v_lshl_add_u32 v5, v156, 2, v0
	ds_read_b32 v5, v5 offset:512
	s_or_b64 exec, exec, s[6:7]
	v_cmp_ge_i32_e64 s[76:77], v184, v18
	v_cmp_lt_i32_e32 vcc, v184, v18
	s_and_saveexec_b64 s[6:7], vcc
	v_lshl_add_u32 v4, v156, 2, v0
	ds_read_b32 v4, v4 offset:768
	s_or_b64 exec, exec, s[6:7]
	v_cmp_ge_i32_e64 s[78:79], v185, v18
	v_cmp_lt_i32_e32 vcc, v185, v18
	v_mov_b32_e32 v6, 0
	v_mov_b32_e32 v7, 0
	s_and_saveexec_b64 s[6:7], vcc
	v_lshl_add_u32 v7, v156, 2, v0
	ds_read_b32 v7, v7 offset:1024
	s_or_b64 exec, exec, s[6:7]
	v_cmp_ge_i32_e64 s[80:81], v186, v18
	v_cmp_lt_i32_e32 vcc, v186, v18
	s_and_saveexec_b64 s[6:7], vcc
	v_lshl_add_u32 v6, v156, 2, v0
	ds_read_b32 v6, v6 offset:1280
	s_or_b64 exec, exec, s[6:7]
	v_cmp_ge_i32_e64 s[82:83], v187, v18
	v_cmp_lt_i32_e32 vcc, v187, v18
	v_mov_b32_e32 v8, 0
	v_mov_b32_e32 v9, 0
	s_and_saveexec_b64 s[6:7], vcc
	v_lshl_add_u32 v9, v156, 2, v0
	ds_read_b32 v9, v9 offset:1536
	s_or_b64 exec, exec, s[6:7]
	v_cmp_ge_i32_e64 s[84:85], v188, v18
	v_cmp_lt_i32_e32 vcc, v188, v18
	s_and_saveexec_b64 s[6:7], vcc
	v_lshl_add_u32 v8, v156, 2, v0
	ds_read_b32 v8, v8 offset:1792
	s_or_b64 exec, exec, s[6:7]
	v_cmp_ge_i32_e64 s[86:87], v189, v18
	v_cmp_lt_i32_e32 vcc, v189, v18
	v_mov_b32_e32 v10, 0
	v_mov_b32_e32 v11, 0
	s_and_saveexec_b64 s[6:7], vcc
	v_lshl_add_u32 v11, v156, 2, v0
	ds_read_b32 v11, v11 offset:2048
	s_or_b64 exec, exec, s[6:7]
	v_cmp_ge_i32_e64 s[88:89], v190, v18
	v_cmp_lt_i32_e32 vcc, v190, v18
	s_and_saveexec_b64 s[6:7], vcc
	v_lshl_add_u32 v10, v156, 2, v0
	ds_read_b32 v10, v10 offset:2304
	s_or_b64 exec, exec, s[6:7]
	v_cmp_ge_i32_e64 s[90:91], v191, v18
	v_cmp_lt_i32_e32 vcc, v191, v18
	v_mov_b32_e32 v12, 0
	v_mov_b32_e32 v13, 0
	s_and_saveexec_b64 s[6:7], vcc
	v_lshl_add_u32 v13, v156, 2, v0
	ds_read_b32 v13, v13 offset:2560
	s_or_b64 exec, exec, s[6:7]
	v_cmp_ge_i32_e64 s[92:93], v219, v18
	v_cmp_lt_i32_e32 vcc, v219, v18
	s_and_saveexec_b64 s[6:7], vcc
	v_lshl_add_u32 v12, v156, 2, v0
	ds_read_b32 v12, v12 offset:2816
	s_or_b64 exec, exec, s[6:7]
	v_cmp_ge_i32_e64 s[94:95], v220, v18
	v_cmp_lt_i32_e32 vcc, v220, v18
	v_mov_b32_e32 v14, 0
	v_mov_b32_e32 v15, 0
	s_and_saveexec_b64 s[6:7], vcc
	v_lshl_add_u32 v15, v156, 2, v0
	ds_read_b32 v15, v15 offset:3072
	s_or_b64 exec, exec, s[6:7]
	v_cmp_ge_i32_e64 s[96:97], v221, v18
	v_cmp_lt_i32_e32 vcc, v221, v18
	s_and_saveexec_b64 s[6:7], vcc
	v_lshl_add_u32 v14, v156, 2, v0
	ds_read_b32 v14, v14 offset:3328
	s_or_b64 exec, exec, s[6:7]
	v_cmp_ge_i32_e64 s[6:7], v222, v18
	v_cmp_lt_i32_e32 vcc, v222, v18
	v_mov_b32_e32 v16, 0
	v_mov_b32_e32 v17, 0
	s_and_saveexec_b64 s[8:9], vcc
	v_lshl_add_u32 v17, v156, 2, v0
	ds_read_b32 v17, v17 offset:3584
	s_or_b64 exec, exec, s[8:9]
	v_cmp_ge_i32_e64 s[8:9], v223, v18
	v_cmp_lt_i32_e32 vcc, v223, v18
	s_and_saveexec_b64 s[12:13], vcc
	v_lshl_add_u32 v16, v156, 2, v0
	ds_read_b32 v16, v16 offset:3840
	s_or_b64 exec, exec, s[12:13]
	v_readfirstlane_b32 s61, v18
	v_mov_b32_e32 v18, 0
	s_mov_b32 s60, 31
	s_cmpk_le_u32 s61, 0x280
	s_cbranch_scc0 .LBB0_503
.Lradix10:
	v_lshl_or_b32 v21, 1, s60, v18
	s_waitcnt lgkmcnt(0)
	v_cmp_ge_u32_e64 s[12:13], v3, v21
	v_cmp_ge_u32_e64 s[14:15], v1, v21
	v_cmp_ge_u32_e64 s[16:17], v5, v21
	v_cmp_ge_u32_e64 s[18:19], v4, v21
	v_cmp_ge_u32_e64 s[20:21], v7, v21
	v_cmp_ge_u32_e64 s[22:23], v6, v21
	v_cmp_ge_u32_e64 s[24:25], v9, v21
	v_cmp_ge_u32_e64 s[26:27], v8, v21
	v_cmp_ge_u32_e64 s[28:29], v11, v21
	v_cmp_ge_u32_e64 s[30:31], v10, v21
	s_bcnt1_i32_b64 s12, s[12:13]
	s_bcnt1_i32_b64 s14, s[14:15]
	s_bcnt1_i32_b64 s16, s[16:17]
	s_bcnt1_i32_b64 s18, s[18:19]
	s_bcnt1_i32_b64 s20, s[20:21]
	s_bcnt1_i32_b64 s22, s[22:23]
	s_bcnt1_i32_b64 s24, s[24:25]
	s_bcnt1_i32_b64 s26, s[26:27]
	s_bcnt1_i32_b64 s28, s[28:29]
	s_bcnt1_i32_b64 s30, s[30:31]
	s_add_i32 s12, s12, s14
	s_add_i32 s16, s16, s18
	s_add_i32 s20, s20, s22
	s_add_i32 s24, s24, s26
	s_add_i32 s28, s28, s30
	s_add_i32 s12, s12, s16
	s_add_i32 s20, s20, s24
	s_add_i32 s12, s12, s20
	s_add_i32 s12, s12, s28
	s_add_i32 s60, s60, -1
	v_cmp_gt_i32_e32 vcc, s12, v20
	s_cmp_eq_u32 s60, -1
	s_nop 0
	v_cndmask_b32_e32 v18, v18, v21, vcc
	s_cbranch_scc0 .Lradix10
	s_branch .Lradix_done

.Lradix_done:
	v_cmp_ge_u32_e64 s[12:13], v3, v18
	v_cmp_ge_u32_e64 s[14:15], v1, v18
	v_cmp_ge_u32_e64 s[16:17], v5, v18
	v_cmp_ge_u32_e64 s[18:19], v4, v18
	v_cmp_ge_u32_e64 s[20:21], v7, v18
	v_cmp_ge_u32_e64 s[22:23], v6, v18
	v_cmp_ge_u32_e64 s[24:25], v9, v18
	v_cmp_ge_u32_e64 s[26:27], v8, v18
	v_cmp_ge_u32_e64 s[28:29], v11, v18
	v_cmp_ge_u32_e64 s[30:31], v10, v18
	v_cmp_ge_u32_e64 s[34:35], v13, v18
	v_cmp_ge_u32_e64 s[36:37], v12, v18
	v_cmp_ge_u32_e64 s[38:39], v15, v18
	v_cmp_ge_u32_e64 s[40:41], v14, v18
	v_cmp_ge_u32_e64 s[66:67], v17, v18
	v_cmp_ge_u32_e32 vcc, v16, v18
	s_bcnt1_i32_b64 s12, s[12:13]
	s_bcnt1_i32_b64 s14, s[14:15]
	s_bcnt1_i32_b64 s16, s[16:17]
	s_bcnt1_i32_b64 s18, s[18:19]
	s_bcnt1_i32_b64 s20, s[20:21]
	s_bcnt1_i32_b64 s22, s[22:23]
	s_bcnt1_i32_b64 s24, s[24:25]
	s_bcnt1_i32_b64 s26, s[26:27]
	s_bcnt1_i32_b64 s28, s[28:29]
	s_bcnt1_i32_b64 s30, s[30:31]
	s_bcnt1_i32_b64 s34, s[34:35]
	s_bcnt1_i32_b64 s36, s[36:37]
	s_bcnt1_i32_b64 s38, s[38:39]
	s_bcnt1_i32_b64 s40, s[40:41]
	s_bcnt1_i32_b64 s66, s[66:67]
	s_bcnt1_i32_b64 s61, vcc
	s_add_i32 s12, s12, s14
	s_add_i32 s16, s16, s18
	s_add_i32 s20, s20, s22
	s_add_i32 s24, s24, s26
	s_add_i32 s28, s28, s30
	s_add_i32 s34, s34, s36
	s_add_i32 s38, s38, s40
	s_add_i32 s66, s66, s61
	s_add_i32 s12, s12, s16
	s_add_i32 s20, s20, s24
	s_add_i32 s28, s28, s34
	s_add_i32 s38, s38, s66
	s_add_i32 s12, s12, s20
	s_add_i32 s28, s28, s38
	s_add_i32 s12, s12, s28
	s_add_i32 s12, s12, -1
	v_cmp_eq_u32_e32 vcc, s12, v20
	s_nop 1
	v_cndmask_b32_e64 v21, 0, 1, vcc
	v_sub_u32_e32 v18, v18, v21
	v_lshlrev_b32_e32 v20, 11, v19
	v_cmp_gt_u32_e32 vcc, v3, v18
	s_movk_i32 s56, 0x420
	s_xor_b64 s[62:63], s[10:11], -1
	v_sub_u32_e32 v20, v0, v20
	v_cmp_gt_u32_e64 s[12:13], v1, v18
	v_cmp_gt_u32_e64 s[14:15], v5, v18
	v_cmp_gt_u32_e64 s[16:17], v4, v18
	v_cmp_gt_u32_e64 s[18:19], v7, v18
	v_cmp_gt_u32_e64 s[20:21], v6, v18
	v_cmp_gt_u32_e64 s[22:23], v9, v18
	v_cmp_gt_u32_e64 s[24:25], v8, v18
	v_cmp_gt_u32_e64 s[26:27], v11, v18
	v_cmp_gt_u32_e64 s[28:29], v10, v18
	v_cmp_gt_u32_e64 s[30:31], v13, v18
	v_cmp_gt_u32_e64 s[34:35], v12, v18
	v_cmp_gt_u32_e64 s[36:37], v15, v18
	v_cmp_gt_u32_e64 s[38:39], v14, v18
	v_cmp_gt_u32_e64 s[40:41], v17, v18
	v_cmp_gt_u32_e64 s[66:67], v16, v18
	v_mul_lo_u32 v0, v19, s56
	s_mov_b64 s[10:11], exec
	v_lshl_add_u32 v19, v156, 1, v20
	s_and_b64 s[60:61], s[62:63], vcc
	s_and_b64 exec, s[10:11], s[60:61]
	ds_read_u16 v100, v19 offset:32768
	s_xor_b64 s[60:61], s[12:13], -1
	s_nor_b64 s[60:61], s[4:5], s[60:61]
	s_and_b64 exec, s[10:11], s[60:61]
	ds_read_u16 v101, v19 offset:32896
	s_xor_b64 s[60:61], s[14:15], -1
	s_nor_b64 s[60:61], s[74:75], s[60:61]
	s_and_b64 exec, s[10:11], s[60:61]
	ds_read_u16 v102, v19 offset:33024
	s_xor_b64 s[60:61], s[16:17], -1
	s_nor_b64 s[60:61], s[76:77], s[60:61]
	s_and_b64 exec, s[10:11], s[60:61]
	ds_read_u16 v103, v19 offset:33152
	s_xor_b64 s[60:61], s[18:19], -1
	s_nor_b64 s[60:61], s[78:79], s[60:61]
	s_and_b64 exec, s[10:11], s[60:61]
	ds_read_u16 v104, v19 offset:33280
	s_xor_b64 s[60:61], s[20:21], -1
	s_nor_b64 s[60:61], s[80:81], s[60:61]
	s_and_b64 exec, s[10:11], s[60:61]
	ds_read_u16 v105, v19 offset:33408
	s_xor_b64 s[60:61], s[22:23], -1
	s_nor_b64 s[60:61], s[82:83], s[60:61]
	s_and_b64 exec, s[10:11], s[60:61]
	ds_read_u16 v106, v19 offset:33536
	s_xor_b64 s[60:61], s[24:25], -1
	s_nor_b64 s[60:61], s[84:85], s[60:61]
	s_and_b64 exec, s[10:11], s[60:61]
	ds_read_u16 v107, v19 offset:33664
	s_xor_b64 s[60:61], s[26:27], -1
	s_nor_b64 s[60:61], s[86:87], s[60:61]
	s_and_b64 exec, s[10:11], s[60:61]
	ds_read_u16 v108, v19 offset:33792
	s_xor_b64 s[60:61], s[28:29], -1
	s_nor_b64 s[60:61], s[88:89], s[60:61]
	s_and_b64 exec, s[10:11], s[60:61]
	ds_read_u16 v109, v19 offset:33920
	s_xor_b64 s[60:61], s[30:31], -1
	s_nor_b64 s[60:61], s[90:91], s[60:61]
	s_and_b64 exec, s[10:11], s[60:61]
	ds_read_u16 v110, v19 offset:34048
	s_xor_b64 s[60:61], s[34:35], -1
	s_nor_b64 s[60:61], s[92:93], s[60:61]
	s_and_b64 exec, s[10:11], s[60:61]
	ds_read_u16 v111, v19 offset:34176
	s_xor_b64 s[60:61], s[36:37], -1
	s_nor_b64 s[60:61], s[94:95], s[60:61]
	s_and_b64 exec, s[10:11], s[60:61]
	ds_read_u16 v112, v19 offset:34304
	s_xor_b64 s[60:61], s[38:39], -1
	s_nor_b64 s[60:61], s[96:97], s[60:61]
	s_and_b64 exec, s[10:11], s[60:61]
	ds_read_u16 v113, v19 offset:34432
	s_xor_b64 s[60:61], s[40:41], -1
	s_nor_b64 s[60:61], s[6:7], s[60:61]
	s_and_b64 exec, s[10:11], s[60:61]
	ds_read_u16 v114, v19 offset:34560
	s_xor_b64 s[60:61], s[66:67], -1
	s_nor_b64 s[60:61], s[8:9], s[60:61]
	s_and_b64 exec, s[10:11], s[60:61]
	ds_read_u16 v115, v19 offset:34688
	s_mov_b64 exec, s[10:11]
	s_waitcnt lgkmcnt(0)
	s_and_b64 s[60:61], s[62:63], vcc
	s_and_b64 exec, s[10:11], s[60:61]
	v_lshrrev_b32_e32 v21, 3, v100
	v_and_b32_e32 v21, 0x1ffc, v21
	v_add_u32_e32 v21, v0, v21
	v_lshlrev_b32_e64 v100, v100, 1
	ds_or_b32 v21, v100 offset:49152
	s_xor_b64 s[60:61], s[12:13], -1
	s_nor_b64 s[60:61], s[4:5], s[60:61]
	s_and_b64 exec, s[10:11], s[60:61]
	v_lshrrev_b32_e32 v21, 3, v101
	v_and_b32_e32 v21, 0x1ffc, v21
	v_add_u32_e32 v21, v0, v21
	v_lshlrev_b32_e64 v101, v101, 1
	ds_or_b32 v21, v101 offset:49152
	s_xor_b64 s[60:61], s[14:15], -1
	s_nor_b64 s[60:61], s[74:75], s[60:61]
	s_and_b64 exec, s[10:11], s[60:61]
	v_lshrrev_b32_e32 v21, 3, v102
	v_and_b32_e32 v21, 0x1ffc, v21
	v_add_u32_e32 v21, v0, v21
	v_lshlrev_b32_e64 v102, v102, 1
	ds_or_b32 v21, v102 offset:49152
	s_xor_b64 s[60:61], s[16:17], -1
	s_nor_b64 s[60:61], s[76:77], s[60:61]
	s_and_b64 exec, s[10:11], s[60:61]
	v_lshrrev_b32_e32 v21, 3, v103
	v_and_b32_e32 v21, 0x1ffc, v21
	v_add_u32_e32 v21, v0, v21
	v_lshlrev_b32_e64 v103, v103, 1
	ds_or_b32 v21, v103 offset:49152
	s_xor_b64 s[60:61], s[18:19], -1
	s_nor_b64 s[60:61], s[78:79], s[60:61]
	s_and_b64 exec, s[10:11], s[60:61]
	v_lshrrev_b32_e32 v21, 3, v104
	v_and_b32_e32 v21, 0x1ffc, v21
	v_add_u32_e32 v21, v0, v21
	v_lshlrev_b32_e64 v104, v104, 1
	ds_or_b32 v21, v104 offset:49152
	s_xor_b64 s[60:61], s[20:21], -1
	s_nor_b64 s[60:61], s[80:81], s[60:61]
	s_and_b64 exec, s[10:11], s[60:61]
	v_lshrrev_b32_e32 v21, 3, v105
	v_and_b32_e32 v21, 0x1ffc, v21
	v_add_u32_e32 v21, v0, v21
	v_lshlrev_b32_e64 v105, v105, 1
	ds_or_b32 v21, v105 offset:49152
	s_xor_b64 s[60:61], s[22:23], -1
	s_nor_b64 s[60:61], s[82:83], s[60:61]
	s_and_b64 exec, s[10:11], s[60:61]
	v_lshrrev_b32_e32 v21, 3, v106
	v_and_b32_e32 v21, 0x1ffc, v21
	v_add_u32_e32 v21, v0, v21
	v_lshlrev_b32_e64 v106, v106, 1
	ds_or_b32 v21, v106 offset:49152
	s_xor_b64 s[60:61], s[24:25], -1
	s_nor_b64 s[60:61], s[84:85], s[60:61]
	s_and_b64 exec, s[10:11], s[60:61]
	v_lshrrev_b32_e32 v21, 3, v107
	v_and_b32_e32 v21, 0x1ffc, v21
	v_add_u32_e32 v21, v0, v21
	v_lshlrev_b32_e64 v107, v107, 1
	ds_or_b32 v21, v107 offset:49152
	s_xor_b64 s[60:61], s[26:27], -1
	s_nor_b64 s[60:61], s[86:87], s[60:61]
	s_and_b64 exec, s[10:11], s[60:61]
	v_lshrrev_b32_e32 v21, 3, v108
	v_and_b32_e32 v21, 0x1ffc, v21
	v_add_u32_e32 v21, v0, v21
	v_lshlrev_b32_e64 v108, v108, 1
	ds_or_b32 v21, v108 offset:49152
	s_xor_b64 s[60:61], s[28:29], -1
	s_nor_b64 s[60:61], s[88:89], s[60:61]
	s_and_b64 exec, s[10:11], s[60:61]
	v_lshrrev_b32_e32 v21, 3, v109
	v_and_b32_e32 v21, 0x1ffc, v21
	v_add_u32_e32 v21, v0, v21
	v_lshlrev_b32_e64 v109, v109, 1
	ds_or_b32 v21, v109 offset:49152
	s_xor_b64 s[60:61], s[30:31], -1
	s_nor_b64 s[60:61], s[90:91], s[60:61]
	s_and_b64 exec, s[10:11], s[60:61]
	v_lshrrev_b32_e32 v21, 3, v110
	v_and_b32_e32 v21, 0x1ffc, v21
	v_add_u32_e32 v21, v0, v21
	v_lshlrev_b32_e64 v110, v110, 1
	ds_or_b32 v21, v110 offset:49152
	s_xor_b64 s[60:61], s[34:35], -1
	s_nor_b64 s[60:61], s[92:93], s[60:61]
	s_and_b64 exec, s[10:11], s[60:61]
	v_lshrrev_b32_e32 v21, 3, v111
	v_and_b32_e32 v21, 0x1ffc, v21
	v_add_u32_e32 v21, v0, v21
	v_lshlrev_b32_e64 v111, v111, 1
	ds_or_b32 v21, v111 offset:49152
	s_xor_b64 s[60:61], s[36:37], -1
	s_nor_b64 s[60:61], s[94:95], s[60:61]
	s_and_b64 exec, s[10:11], s[60:61]
	v_lshrrev_b32_e32 v21, 3, v112
	v_and_b32_e32 v21, 0x1ffc, v21
	v_add_u32_e32 v21, v0, v21
	v_lshlrev_b32_e64 v112, v112, 1
	ds_or_b32 v21, v112 offset:49152
	s_xor_b64 s[60:61], s[38:39], -1
	s_nor_b64 s[60:61], s[96:97], s[60:61]
	s_and_b64 exec, s[10:11], s[60:61]
	v_lshrrev_b32_e32 v21, 3, v113
	v_and_b32_e32 v21, 0x1ffc, v21
	v_add_u32_e32 v21, v0, v21
	v_lshlrev_b32_e64 v113, v113, 1
	ds_or_b32 v21, v113 offset:49152
	s_xor_b64 s[60:61], s[40:41], -1
	s_nor_b64 s[60:61], s[6:7], s[60:61]
	s_and_b64 exec, s[10:11], s[60:61]
	v_lshrrev_b32_e32 v21, 3, v114
	v_and_b32_e32 v21, 0x1ffc, v21
	v_add_u32_e32 v21, v0, v21
	v_lshlrev_b32_e64 v114, v114, 1
	ds_or_b32 v21, v114 offset:49152
	s_xor_b64 s[60:61], s[66:67], -1
	s_nor_b64 s[60:61], s[8:9], s[60:61]
	s_and_b64 exec, s[10:11], s[60:61]
	v_lshrrev_b32_e32 v21, 3, v115
	v_and_b32_e32 v21, 0x1ffc, v21
	v_add_u32_e32 v21, v0, v21
	v_lshlrev_b32_e64 v115, v115, 1
	ds_or_b32 v21, v115 offset:49152
	s_mov_b64 exec, s[10:11]
	s_bcnt1_i32_b64 s10, vcc
	s_bcnt1_i32_b64 s11, s[12:13]
	s_bcnt1_i32_b64 s12, s[14:15]
	s_add_i32 s10, s10, s11
	s_bcnt1_i32_b64 s13, s[16:17]
	s_add_i32 s10, s10, s12
	s_bcnt1_i32_b64 s14, s[18:19]
	s_add_i32 s10, s10, s13
	s_bcnt1_i32_b64 s15, s[20:21]
	s_add_i32 s10, s10, s14
	s_bcnt1_i32_b64 s16, s[22:23]
	s_add_i32 s10, s10, s15
	s_bcnt1_i32_b64 s17, s[24:25]
	s_add_i32 s10, s10, s16
	s_bcnt1_i32_b64 s18, s[26:27]
	s_add_i32 s10, s10, s17
	s_bcnt1_i32_b64 s19, s[28:29]
	s_add_i32 s10, s10, s18
	s_bcnt1_i32_b64 s20, s[30:31]
	s_add_i32 s10, s10, s19
	s_bcnt1_i32_b64 s21, s[34:35]
	s_add_i32 s10, s10, s20
	s_bcnt1_i32_b64 s22, s[36:37]
	s_add_i32 s10, s10, s21
	s_bcnt1_i32_b64 s23, s[38:39]
	s_add_i32 s10, s10, s22
	s_bcnt1_i32_b64 s24, s[40:41]
	s_add_i32 s10, s10, s23
	s_bcnt1_i32_b64 s25, s[66:67]
	s_add_i32 s10, s10, s24
	s_add_i32 s10, s10, s25
	v_subrev_u32_e32 v2, s10, v2
	v_cmp_lt_i32_e32 vcc, 0, v2
	s_and_saveexec_b64 s[60:61], vcc
	s_cbranch_execz .LBB0_462
	v_cmp_eq_u32_e64 s[10:11], v1, v18
	s_xor_b64 s[4:5], s[4:5], -1
	v_cmp_eq_u32_e64 s[12:13], v5, v18
	s_and_b64 s[10:11], s[4:5], s[10:11]
	s_xor_b64 s[4:5], s[74:75], -1
	v_cmp_eq_u32_e64 s[14:15], v4, v18
	s_and_b64 s[12:13], s[4:5], s[12:13]
	s_xor_b64 s[4:5], s[76:77], -1
	v_cmp_eq_u32_e64 s[16:17], v7, v18
	s_and_b64 s[14:15], s[4:5], s[14:15]
	s_xor_b64 s[4:5], s[78:79], -1
	v_cmp_eq_u32_e64 s[18:19], v6, v18
	s_and_b64 s[16:17], s[4:5], s[16:17]
	s_xor_b64 s[4:5], s[80:81], -1
	v_cmp_eq_u32_e64 s[20:21], v9, v18
	s_and_b64 s[18:19], s[4:5], s[18:19]
	s_xor_b64 s[4:5], s[82:83], -1
	v_cmp_eq_u32_e64 s[22:23], v8, v18
	s_and_b64 s[20:21], s[4:5], s[20:21]
	s_xor_b64 s[4:5], s[84:85], -1
	v_cmp_eq_u32_e64 s[24:25], v11, v18
	s_and_b64 s[22:23], s[4:5], s[22:23]
	s_xor_b64 s[4:5], s[86:87], -1
	v_cmp_eq_u32_e64 s[26:27], v10, v18
	v_cmp_lt_i32_e64 s[66:67], v202, v201
	s_and_b64 s[24:25], s[4:5], s[24:25]
	s_xor_b64 s[4:5], s[88:89], -1
	v_cmp_eq_u32_e64 s[28:29], v13, v18
	v_cndmask_b32_e64 v1, v199, v202, s[66:67]
	v_cmp_lt_i32_e64 s[66:67], v203, v201
	s_and_b64 s[26:27], s[4:5], s[26:27]
	s_xor_b64 s[4:5], s[90:91], -1
	v_cmp_eq_u32_e64 s[30:31], v12, v18
	v_cndmask_b32_e64 v4, v199, v203, s[66:67]
	v_cmp_lt_i32_e64 s[66:67], v204, v201
	s_and_b64 s[28:29], s[4:5], s[28:29]
	s_xor_b64 s[4:5], s[92:93], -1
	v_cmp_eq_u32_e64 s[34:35], v15, v18
	v_cndmask_b32_e64 v5, v199, v204, s[66:67]
	v_cmp_lt_i32_e64 s[66:67], v205, v201
	s_and_b64 s[30:31], s[4:5], s[30:31]
	s_xor_b64 s[4:5], s[94:95], -1
	v_cmp_eq_u32_e64 s[36:37], v14, v18
	v_cndmask_b32_e64 v6, v199, v205, s[66:67]
	v_cmp_lt_i32_e64 s[66:67], v206, v201
	s_and_b64 s[34:35], s[4:5], s[34:35]
	s_xor_b64 s[4:5], s[96:97], -1
	v_cmp_eq_u32_e64 s[38:39], v17, v18
	v_cndmask_b32_e64 v7, v199, v206, s[66:67]
	v_cmp_lt_i32_e64 s[66:67], v207, v201
	s_and_b64 s[36:37], s[4:5], s[36:37]
	s_xor_b64 s[4:5], s[6:7], -1
	v_cmp_eq_u32_e32 vcc, v3, v18
	v_cmp_eq_u32_e64 s[40:41], v16, v18
	v_cndmask_b32_e64 v8, v199, v207, s[66:67]
	s_and_b64 s[6:7], s[4:5], s[38:39]
	s_xor_b64 s[4:5], s[8:9], -1
	v_mov_b32_e32 v19, -1
	s_mov_b32 s56, 1
	v_lshl_add_u32 v3, v156, 1, v20
	v_lshlrev_b32_e32 v1, 2, v1
	v_lshlrev_b32_e32 v4, 2, v4
	v_lshlrev_b32_e32 v5, 2, v5
	v_lshlrev_b32_e32 v6, 2, v6
	v_lshlrev_b32_e32 v7, 2, v7
	v_lshlrev_b32_e32 v8, 2, v8
	s_and_b64 s[62:63], s[62:63], vcc
	s_and_b64 s[8:9], s[4:5], s[40:41]
	s_mov_b64 s[38:39], 0
	s_branch .LBB0_539
